# v36 with s_sleep 3 (was 1) in the 4 main-loop barrier poll loops: looser polling, less contention on the barrier flags
# baseline (speedup 1.0000x reference)
.LBB0_806:
	global_load_dword v15, v159, s[28:29] sc1
	s_waitcnt lgkmcnt(0)
	global_load_dword v0, v159, s[30:31] sc1
	global_load_dword v1, v159, s[34:35] sc1
	global_load_dword v2, v159, s[36:37] sc1
	global_load_dword v3, v159, s[38:39] sc1
	global_load_dword v4, v159, s[42:43] sc1
	global_load_dword v5, v159, s[44:45] sc1
	global_load_dword v6, v159, s[46:47] sc1
	global_load_dword v7, v159, s[48:49] sc1
	global_load_dword v8, v159, s[50:51] sc1
	global_load_dword v9, v159, s[60:61] sc1
	global_load_dword v10, v159, s[62:63] sc1
	global_load_dword v11, v159, s[64:65] sc1
	global_load_dword v12, v159, s[76:77] sc1
	global_load_dword v13, v159, s[78:79] sc1
	global_load_dword v14, v159, s[80:81] sc1
	s_mov_b64 s[2:3], -1
	s_mov_b64 s[4:5], -1
	s_waitcnt vmcnt(14)
	v_add_u32_e32 v16, v0, v15
	s_waitcnt vmcnt(13)
	v_add_u32_e32 v16, v16, v1
	s_waitcnt vmcnt(12)
	v_add_u32_e32 v16, v16, v2
	s_waitcnt vmcnt(11)
	v_add_u32_e32 v16, v16, v3
	s_waitcnt vmcnt(10)
	v_add_u32_e32 v16, v16, v4
	s_waitcnt vmcnt(9)
	v_add_u32_e32 v16, v16, v5
	s_waitcnt vmcnt(8)
	v_add_u32_e32 v16, v16, v6
	s_waitcnt vmcnt(7)
	v_add_u32_e32 v16, v16, v7
	s_waitcnt vmcnt(6)
	v_add_u32_e32 v16, v16, v8
	s_waitcnt vmcnt(5)
	v_add_u32_e32 v16, v16, v9
	s_waitcnt vmcnt(4)
	v_add_u32_e32 v16, v16, v10
	s_waitcnt vmcnt(3)
	v_add_u32_e32 v16, v16, v11
	s_waitcnt vmcnt(2)
	v_add_u32_e32 v16, v16, v12
	s_waitcnt vmcnt(1)
	v_add_u32_e32 v16, v16, v13
	s_waitcnt vmcnt(0)
	v_add_u32_e32 v16, v16, v14
	v_cmp_eq_u32_e32 vcc, s24, v16
	s_cbranch_vccnz .LBB0_805
	s_and_b32 s2, s8, 0xff
	s_cmp_eq_u32 s2, 0
	s_mov_b64 s[2:3], -1
	s_mov_b64 s[6:7], -1
	s_sleep 3
	s_cbranch_scc0 .LBB0_810
	global_load_dword v16, v159, s[26:27] sc1
	s_waitcnt vmcnt(0)
	v_cmp_eq_u32_e32 vcc, 0, v16
	s_cbranch_vccnz .LBB0_812
	s_mov_b64 s[6:7], 0

.LBB0_824:
	s_and_b32 s18, s8, 0xff
	s_mov_b64 s[16:17], -1
	s_cmp_lg_u32 s18, 0
	s_mov_b64 s[20:21], -1
	s_sleep 3
	s_cbranch_scc1 .LBB0_827
	global_load_dword v0, v159, s[26:27] sc1
	s_waitcnt vmcnt(0)
	v_cmp_eq_u32_e32 vcc, 0, v0
	s_cbranch_vccnz .LBB0_829
	s_mov_b64 s[20:21], 0
	s_mov_b64 s[18:19], -1
